# phase 2: half of the workgroups (bit 3 of the workgroup id) run their gmlp units before their attention unit, so memory-heavy and latency-bound work overlap across the chip
# speedup vs baseline: 1.0092x; 1.0011x over previous
.LBB0_753:
	s_cmp_lt_i32 s94, 3
	s_cselect_b64 s[42:43], -1, 0
	s_and_b64 s[0:1], s[42:43], s[2:3]
	s_andn2_b64 vcc, exec, s[0:1]
	s_cbranch_vccnz .LBB0_800
	s_bfe_u32 s98, s97, 0x10003
	s_nop 0
	v_writelane_b32 v255, s98, 41
	s_nop 3
.Lp2_top:
	v_readlane_b32 s98, v255, 41
	s_nop 3
	s_cmp_eq_u32 s98, 1
	s_cbranch_scc1 .Lp2_gmlp
	s_cmpk_gt_i32 s97, 0xff
	s_cbranch_scc1 .LBB0_784
	v_mbcnt_lo_u32_b32 v20, -1, 0
	v_mbcnt_hi_u32_b32 v20, -1, v20
	v_and_b32_e32 v22, 64, v20
	v_xor_b32_e32 v21, 1, v20
	v_add_u32_e32 v23, 64, v22
	v_cmp_lt_i32_e32 vcc, v21, v23
	s_movk_i32 s0, 0x7f
	v_cmp_gt_u32_sdwa s[16:17], v0, s0 src0_sel:BYTE_0 src1_sel:DWORD
	v_cndmask_b32_e32 v21, v20, v21, vcc
	v_lshlrev_b32_e32 v98, 2, v21
	v_xor_b32_e32 v21, 2, v20
	v_cmp_lt_i32_e32 vcc, v21, v23
	s_movk_i32 s0, 0x1ff
	v_cmp_lt_u32_e64 s[2:3], s0, v0
	v_cndmask_b32_e32 v21, v20, v21, vcc
	v_lshlrev_b32_e32 v99, 2, v21
	v_xor_b32_e32 v21, 4, v20
	v_cmp_lt_i32_e32 vcc, v21, v23
	s_add_i32 s0, 0, 0x11400
	v_lshrrev_b32_e32 v1, 6, v0
	v_cndmask_b32_e32 v21, v20, v21, vcc
	v_lshlrev_b32_e32 v100, 2, v21
	v_xor_b32_e32 v21, 8, v20
	s_movk_i32 s1, 0x1500
	v_mov_b32_e32 v13, s0
	v_cmp_lt_i32_e32 vcc, v21, v23
	v_and_b32_e32 v97, 15, v0
	v_mad_u32_u24 v13, v1, s1, v13
	v_cndmask_b32_e32 v20, v20, v21, vcc
	s_movk_i32 s0, 0x150
	s_waitcnt lgkmcnt(0)
	v_mov_b32_e32 v4, 1
	v_or_b32_e32 v6, 0x200, v0
	v_or_b32_e32 v8, 0x400, v0
	v_or_b32_e32 v10, 0x600, v0
	v_bfe_u32 v12, v0, 4, 2
	v_lshlrev_b32_e32 v101, 2, v20
	v_lshl_add_u32 v20, v97, 1, v13
	v_mad_u32_u24 v21, v97, s0, v13
	v_lshlrev_b32_e32 v13, 2, v0
	v_lshlrev_b32_sdwa v5, v4, v0 dst_sel:DWORD dst_unused:UNUSED_PAD src0_sel:DWORD src1_sel:BYTE_0
	v_mov_b32_e32 v55, 0
	v_lshrrev_b32_e32 v4, 5, v0
	v_lshrrev_b32_e32 v94, 3, v6
	v_lshrrev_b32_e32 v6, 5, v6
	v_lshrrev_b32_e32 v95, 3, v8
	v_lshrrev_b32_e32 v8, 5, v8
	v_lshrrev_b32_e32 v96, 3, v10
	v_lshrrev_b32_e32 v10, 5, v10
	v_lshlrev_b32_e32 v58, 2, v12
	v_and_or_b32 v13, v13, 48, v22
	v_and_b32_e32 v2, 7, v0
	v_lshrrev_b32_e32 v59, 3, v0
	v_and_b32_e32 v4, 8, v4
	s_movk_i32 s14, 0x210
	v_and_b32_e32 v6, 24, v6
	v_and_b32_e32 v8, 40, v8
	v_and_b32_e32 v10, 56, v10
	v_lshlrev_b32_e32 v56, 3, v12
	v_mov_b32_e32 v57, v55
	v_lshlrev_b32_e32 v102, 2, v13
	v_or_b32_e32 v13, 1, v58
	v_or_b32_e32 v22, 2, v58
	v_or_b32_e32 v23, 3, v58
	v_lshl_add_u32 v3, v2, 4, 0
	v_lshlrev_b32_e32 v2, 3, v2
	v_mul_u32_u24_e32 v7, 0x90, v59
	v_mad_u32_u24 v9, v4, s14, 0
	v_mul_u32_u24_e32 v11, 0x90, v94
	v_mad_u32_u24 v14, v6, s14, 0
	v_mul_u32_u24_e32 v15, 0x90, v95
	v_mad_u32_u24 v16, v8, s14, 0
	v_mul_u32_u24_e32 v17, 0x90, v96
	v_mad_u32_u24 v18, v10, s14, 0
	v_lshlrev_b32_e32 v19, 4, v12
	v_and_b32_e32 v103, 3, v0
	v_cmp_gt_u32_e64 s[8:9], v97, v13
	v_cmp_gt_u32_e64 s[10:11], v97, v22
	v_cmp_gt_u32_e64 s[12:13], v97, v23
	v_mul_u32_u24_e32 v22, 0x540, v12
	v_mul_u32_u24_e32 v23, 0x150, v13
	s_add_u32 s18, s92, 0xe400000
	v_lshl_add_u64 v[12:13], s[92:93], 0, v[56:57]
	s_mov_b64 s[0:1], 0x6400000
	s_mov_b32 s15, 0
	s_movk_i32 s33, 0x90
	v_cmp_eq_u32_e64 s[4:5], 2, v103
	v_cmp_gt_u32_e64 s[6:7], v97, v58
	v_or_b32_e32 v104, 16, v97
	v_or_b32_e32 v105, 32, v97
	v_or_b32_e32 v106, 48, v97
	v_or_b32_e32 v107, 64, v97
	v_or_b32_e32 v108, 0x50, v97
	v_or_b32_e32 v109, 0x60, v97
	v_or_b32_e32 v110, 0x70, v97
	v_or_b32_e32 v111, 0x90, v97
	s_addc_u32 s19, s93, 0
	v_lshl_add_u64 v[60:61], v[12:13], 0, s[0:1]
	v_add_u32_e32 v57, 0, v19
	v_mad_u32_u24 v112, v97, s14, 0
	s_movk_i32 s36, 0x2a00
	v_add_u32_e32 v113, v3, v7
	v_lshlrev_b32_e32 v62, 1, v4
	v_add_u32_e32 v114, v9, v5
	v_add_u32_e32 v115, v3, v11
	v_lshlrev_b32_e32 v64, 1, v6
	v_add_u32_e32 v116, v14, v5
	v_lshlrev_b32_e32 v66, 1, v2
	v_add_u32_e32 v117, v3, v15
	v_lshlrev_b32_e32 v68, 1, v8
	v_add_u32_e32 v118, v16, v5
	v_add_u32_e32 v119, v3, v17
	v_lshlrev_b32_e32 v70, 1, v10
	v_add_u32_e32 v120, v18, v5
	v_lshlrev_b32_e32 v72, 1, v58
	s_mov_b32 s37, 0xf149f2ca
	v_add_u32_e32 v121, v20, v22
	v_add_u32_e32 v122, v20, v23
	v_add_u32_e32 v123, v21, v19
	v_mov_b32_e32 v124, 0xf149f2ca
	s_mov_b32 s38, s97
	s_branch .LBB0_757

.LBB0_784:
	v_readlane_b32 s98, v255, 41
	s_nop 3
	s_cmp_eq_u32 s98, 2
	s_cbranch_scc1 .LBB0_800

.Lgm_mdone:
	s_waitcnt lgkmcnt(0)
	s_barrier
	s_nop 7
	v_lshlrev_b32_e32 v224, 16, v128
	v_and_b32_e32 v225, 0xffff0000, v128
	v_lshlrev_b32_e32 v226, 16, v129
	v_and_b32_e32 v227, 0xffff0000, v129
	v_lshlrev_b32_e32 v228, 16, v144
	v_and_b32_e32 v229, 0xffff0000, v144
	v_lshlrev_b32_e32 v230, 16, v145
	v_and_b32_e32 v231, 0xffff0000, v145
	v_add_f32_e32 v192, v192, v10
	v_add_f32_e32 v193, v193, v10
	v_add_f32_e32 v194, v194, v10
	v_add_f32_e32 v195, v195, v10
	v_mul_f32_e32 v192, v224, v192
	v_mul_f32_e32 v193, v225, v193
	v_mul_f32_e32 v194, v226, v194
	v_mul_f32_e32 v195, v227, v195
	v_mul_f32_e32 v192, v192, v228
	v_mul_f32_e32 v193, v193, v229
	v_mul_f32_e32 v194, v194, v230
	v_mul_f32_e32 v195, v195, v231
	v_lshlrev_b32_e32 v224, 16, v130
	v_and_b32_e32 v225, 0xffff0000, v130
	v_lshlrev_b32_e32 v226, 16, v131
	v_and_b32_e32 v227, 0xffff0000, v131
	v_lshlrev_b32_e32 v228, 16, v146
	v_and_b32_e32 v229, 0xffff0000, v146
	v_lshlrev_b32_e32 v230, 16, v147
	v_and_b32_e32 v231, 0xffff0000, v147
	v_add_f32_e32 v196, v196, v10
	v_add_f32_e32 v197, v197, v10
	v_add_f32_e32 v198, v198, v10
	v_add_f32_e32 v199, v199, v10
	v_mul_f32_e32 v196, v224, v196
	v_mul_f32_e32 v197, v225, v197
	v_mul_f32_e32 v198, v226, v198
	v_mul_f32_e32 v199, v227, v199
	v_mul_f32_e32 v196, v196, v228
	v_mul_f32_e32 v197, v197, v229
	v_mul_f32_e32 v198, v198, v230
	v_mul_f32_e32 v199, v199, v231
	v_cvt_pk_bf16_f32 v192, v192, v193
	v_cvt_pk_bf16_f32 v193, v194, v195
	v_cvt_pk_bf16_f32 v194, v196, v197
	v_cvt_pk_bf16_f32 v195, v198, v199
	global_store_dwordx4 v8, v[192:195], s[18:19]
	v_lshlrev_b32_e32 v224, 16, v132
	v_and_b32_e32 v225, 0xffff0000, v132
	v_lshlrev_b32_e32 v226, 16, v133
	v_and_b32_e32 v227, 0xffff0000, v133
	v_lshlrev_b32_e32 v228, 16, v148
	v_and_b32_e32 v229, 0xffff0000, v148
	v_lshlrev_b32_e32 v230, 16, v149
	v_and_b32_e32 v231, 0xffff0000, v149
	v_add_f32_e32 v200, v200, v10
	v_add_f32_e32 v201, v201, v10
	v_add_f32_e32 v202, v202, v10
	v_add_f32_e32 v203, v203, v10
	v_mul_f32_e32 v200, v224, v200
	v_mul_f32_e32 v201, v225, v201
	v_mul_f32_e32 v202, v226, v202
	v_mul_f32_e32 v203, v227, v203
	v_mul_f32_e32 v200, v200, v228
	v_mul_f32_e32 v201, v201, v229
	v_mul_f32_e32 v202, v202, v230
	v_mul_f32_e32 v203, v203, v231
	v_lshlrev_b32_e32 v224, 16, v134
	v_and_b32_e32 v225, 0xffff0000, v134
	v_lshlrev_b32_e32 v226, 16, v135
	v_and_b32_e32 v227, 0xffff0000, v135
	v_lshlrev_b32_e32 v228, 16, v150
	v_and_b32_e32 v229, 0xffff0000, v150
	v_lshlrev_b32_e32 v230, 16, v151
	v_and_b32_e32 v231, 0xffff0000, v151
	v_add_f32_e32 v204, v204, v10
	v_add_f32_e32 v205, v205, v10
	v_add_f32_e32 v206, v206, v10
	v_add_f32_e32 v207, v207, v10
	v_mul_f32_e32 v204, v224, v204
	v_mul_f32_e32 v205, v225, v205
	v_mul_f32_e32 v206, v226, v206
	v_mul_f32_e32 v207, v227, v207
	v_mul_f32_e32 v204, v204, v228
	v_mul_f32_e32 v205, v205, v229
	v_mul_f32_e32 v206, v206, v230
	v_mul_f32_e32 v207, v207, v231
	v_cvt_pk_bf16_f32 v200, v200, v201
	v_cvt_pk_bf16_f32 v201, v202, v203
	v_cvt_pk_bf16_f32 v202, v204, v205
	v_cvt_pk_bf16_f32 v203, v206, v207
	global_store_dwordx4 v8, v[200:203], s[18:19] offset:64
	v_lshlrev_b32_e32 v224, 16, v136
	v_and_b32_e32 v225, 0xffff0000, v136
	v_lshlrev_b32_e32 v226, 16, v137
	v_and_b32_e32 v227, 0xffff0000, v137
	v_lshlrev_b32_e32 v228, 16, v152
	v_and_b32_e32 v229, 0xffff0000, v152
	v_lshlrev_b32_e32 v230, 16, v153
	v_and_b32_e32 v231, 0xffff0000, v153
	v_add_f32_e32 v208, v208, v10
	v_add_f32_e32 v209, v209, v10
	v_add_f32_e32 v210, v210, v10
	v_add_f32_e32 v211, v211, v10
	v_mul_f32_e32 v208, v224, v208
	v_mul_f32_e32 v209, v225, v209
	v_mul_f32_e32 v210, v226, v210
	v_mul_f32_e32 v211, v227, v211
	v_mul_f32_e32 v208, v208, v228
	v_mul_f32_e32 v209, v209, v229
	v_mul_f32_e32 v210, v210, v230
	v_mul_f32_e32 v211, v211, v231
	v_lshlrev_b32_e32 v224, 16, v138
	v_and_b32_e32 v225, 0xffff0000, v138
	v_lshlrev_b32_e32 v226, 16, v139
	v_and_b32_e32 v227, 0xffff0000, v139
	v_lshlrev_b32_e32 v228, 16, v154
	v_and_b32_e32 v229, 0xffff0000, v154
	v_lshlrev_b32_e32 v230, 16, v155
	v_and_b32_e32 v231, 0xffff0000, v155
	v_add_f32_e32 v212, v212, v10
	v_add_f32_e32 v213, v213, v10
	v_add_f32_e32 v214, v214, v10
	v_add_f32_e32 v215, v215, v10
	v_mul_f32_e32 v212, v224, v212
	v_mul_f32_e32 v213, v225, v213
	v_mul_f32_e32 v214, v226, v214
	v_mul_f32_e32 v215, v227, v215
	v_mul_f32_e32 v212, v212, v228
	v_mul_f32_e32 v213, v213, v229
	v_mul_f32_e32 v214, v214, v230
	v_mul_f32_e32 v215, v215, v231
	v_cvt_pk_bf16_f32 v208, v208, v209
	v_cvt_pk_bf16_f32 v209, v210, v211
	v_cvt_pk_bf16_f32 v210, v212, v213
	v_cvt_pk_bf16_f32 v211, v214, v215
	global_store_dwordx4 v8, v[208:211], s[18:19] offset:128
	v_lshlrev_b32_e32 v224, 16, v140
	v_and_b32_e32 v225, 0xffff0000, v140
	v_lshlrev_b32_e32 v226, 16, v141
	v_and_b32_e32 v227, 0xffff0000, v141
	v_lshlrev_b32_e32 v228, 16, v156
	v_and_b32_e32 v229, 0xffff0000, v156
	v_lshlrev_b32_e32 v230, 16, v157
	v_and_b32_e32 v231, 0xffff0000, v157
	v_add_f32_e32 v216, v216, v10
	v_add_f32_e32 v217, v217, v10
	v_add_f32_e32 v218, v218, v10
	v_add_f32_e32 v219, v219, v10
	v_mul_f32_e32 v216, v224, v216
	v_mul_f32_e32 v217, v225, v217
	v_mul_f32_e32 v218, v226, v218
	v_mul_f32_e32 v219, v227, v219
	v_mul_f32_e32 v216, v216, v228
	v_mul_f32_e32 v217, v217, v229
	v_mul_f32_e32 v218, v218, v230
	v_mul_f32_e32 v219, v219, v231
	v_lshlrev_b32_e32 v224, 16, v142
	v_and_b32_e32 v225, 0xffff0000, v142
	v_lshlrev_b32_e32 v226, 16, v143
	v_and_b32_e32 v227, 0xffff0000, v143
	v_lshlrev_b32_e32 v228, 16, v158
	v_and_b32_e32 v229, 0xffff0000, v158
	v_lshlrev_b32_e32 v230, 16, v159
	v_and_b32_e32 v231, 0xffff0000, v159
	v_add_f32_e32 v220, v220, v10
	v_add_f32_e32 v221, v221, v10
	v_add_f32_e32 v222, v222, v10
	v_add_f32_e32 v223, v223, v10
	v_mul_f32_e32 v220, v224, v220
	v_mul_f32_e32 v221, v225, v221
	v_mul_f32_e32 v222, v226, v222
	v_mul_f32_e32 v223, v227, v223
	v_mul_f32_e32 v220, v220, v228
	v_mul_f32_e32 v221, v221, v229
	v_mul_f32_e32 v222, v222, v230
	v_mul_f32_e32 v223, v223, v231
	v_cvt_pk_bf16_f32 v216, v216, v217
	v_cvt_pk_bf16_f32 v217, v218, v219
	v_cvt_pk_bf16_f32 v218, v220, v221
	v_cvt_pk_bf16_f32 v219, v222, v223
	global_store_dwordx4 v8, v[216:219], s[18:19] offset:192
	s_waitcnt vmcnt(4)
	v_mov_b32_e32 v92, v112
	v_mov_b32_e32 v93, v113
	v_mov_b32_e32 v94, v114
	v_mov_b32_e32 v95, v115
	v_mov_b32_e32 v96, v116
	v_mov_b32_e32 v97, v117
	v_mov_b32_e32 v98, v118
	v_mov_b32_e32 v99, v119
	v_mov_b32_e32 v100, v120
	v_mov_b32_e32 v101, v121
	v_mov_b32_e32 v102, v122
	v_mov_b32_e32 v103, v123
	v_mov_b32_e32 v104, v124
	v_mov_b32_e32 v105, v125
	v_mov_b32_e32 v106, v126
	v_mov_b32_e32 v107, v127
	v_mov_b32_e32 v36, v40
	v_mov_b32_e32 v37, v41
	v_mov_b32_e32 v38, v42
	v_mov_b32_e32 v39, v43
	v_mov_b32_e32 v128, v160
	v_mov_b32_e32 v129, v161
	v_mov_b32_e32 v130, v162
	v_mov_b32_e32 v131, v163
	v_mov_b32_e32 v132, v164
	v_mov_b32_e32 v133, v165
	v_mov_b32_e32 v134, v166
	v_mov_b32_e32 v135, v167
	v_mov_b32_e32 v136, v168
	v_mov_b32_e32 v137, v169
	v_mov_b32_e32 v138, v170
	v_mov_b32_e32 v139, v171
	v_mov_b32_e32 v140, v172
	v_mov_b32_e32 v141, v173
	v_mov_b32_e32 v142, v174
	v_mov_b32_e32 v143, v175
	v_mov_b32_e32 v144, v176
	v_mov_b32_e32 v145, v177
	v_mov_b32_e32 v146, v178
	v_mov_b32_e32 v147, v179
	v_mov_b32_e32 v148, v180
	v_mov_b32_e32 v149, v181
	v_mov_b32_e32 v150, v182
	v_mov_b32_e32 v151, v183
	v_mov_b32_e32 v152, v184
	v_mov_b32_e32 v153, v185
	v_mov_b32_e32 v154, v186
	v_mov_b32_e32 v155, v187
	v_mov_b32_e32 v156, v188
	v_mov_b32_e32 v157, v189
	v_mov_b32_e32 v158, v190
	v_mov_b32_e32 v159, v191
	s_lshr_b32 s9, s29, 3
	s_lshl_b32 s27, s9, 19
	s_add_u32 s18, s22, s27
	s_addc_u32 s19, s23, 0
	s_add_i32 s8, s8, s96
	s_cmpk_lt_i32 s8, 0x400
	s_cbranch_scc1 .Lgm_loop
	v_readlane_b32 s98, v255, 41
	s_nop 3
	s_cmp_eq_u32 s98, 1
	s_cbranch_scc0 .Lp2_done
	s_mov_b32 s98, 2
	s_nop 0
	v_writelane_b32 v255, s98, 41
	s_waitcnt vmcnt(0) lgkmcnt(0)
	s_barrier
	s_branch .Lp2_top
.Lp2_done:
.LBB0_800:
	s_cmp_gt_i32 s95, 3
	s_cselect_b64 s[2:3], -1, 0
	s_and_b64 s[0:1], s[42:43], s[2:3]
	s_andn2_b64 vcc, exec, s[0:1]
	s_cbranch_vccnz .LBB0_854
	s_waitcnt vmcnt(0)
	s_waitcnt vmcnt(0) lgkmcnt(0)
	s_barrier
	s_mov_b64 s[0:1], exec
	v_readlane_b32 s4, v255, 10
	v_readlane_b32 s5, v255, 11
	s_and_b64 s[4:5], s[0:1], s[4:5]
	s_mov_b64 exec, s[4:5]
	s_cbranch_execz .LBB0_853
	s_add_i32 s4, 0, 0x20000
	v_mov_b32_e32 v1, s4
	s_waitcnt vmcnt(0) expcnt(0) lgkmcnt(0)
	ds_read_b32 v3, v1
	s_add_i32 s4, 0, 0x20004
	v_mov_b32_e32 v1, s4
	ds_read_b32 v1, v1
	s_waitcnt lgkmcnt(1)
	v_cmp_ne_u32_e32 vcc, 0, v3
	s_cbranch_vccnz .LBB0_817
	v_readlane_b32 s4, v255, 8
	v_readlane_b32 s5, v255, 9
	s_load_dwordx2 s[8:9], s[4:5], 0x4
	s_add_u32 s4, s92, 0x1cf10200
	s_addc_u32 s5, s93, 0
	s_add_u32 s6, s92, 0x1cf10400
	s_addc_u32 s7, s93, 0
	s_waitcnt lgkmcnt(0)
	s_mul_i32 s33, s8, s96
	s_add_u32 s8, s92, 0x1cf10500
	s_mul_i32 s33, s33, s9
	s_addc_u32 s9, s93, 0
	s_add_u32 s10, s92, 0x1cf10600
	s_addc_u32 s11, s93, 0
	s_add_u32 s12, s92, 0x1cf10700
	s_addc_u32 s13, s93, 0
	s_add_u32 s14, s92, 0x1cf10800
	s_addc_u32 s15, s93, 0
	s_add_u32 s16, s92, 0x1cf10900
	s_addc_u32 s17, s93, 0
	s_add_u32 s18, s92, 0x1cf10a00
	s_addc_u32 s19, s93, 0
	s_add_u32 s20, s92, 0x1cf10b00
	s_addc_u32 s21, s93, 0
	s_add_u32 s22, s92, 0x1cf10c00
	s_addc_u32 s23, s93, 0
	s_add_u32 s24, s92, 0x1cf10d00
	s_addc_u32 s25, s93, 0
	s_add_u32 s26, s92, 0x1cf10e00
	s_addc_u32 s27, s93, 0
	s_add_u32 s28, s92, 0x1cf10f00
	s_addc_u32 s29, s93, 0
	s_add_u32 s30, s92, 0x1cf11000
	s_addc_u32 s31, s93, 0
	s_add_u32 s34, s92, 0x1cf11100
	s_addc_u32 s35, s93, 0
	s_add_u32 s36, s92, 0x1cf11200
	s_addc_u32 s37, s93, 0
	s_add_u32 s38, s92, 0x1cf11300
	s_addc_u32 s39, s93, 0
	s_mov_b32 s46, 1
	v_mov_b32_e32 v17, 0
	s_branch .LBB0_805
